# P1 epilogue NRB passes: table and gain loads hoisted above the ds_bpermute reduction chain (latency overlap)
# baseline (speedup 1.0000x reference)
.LBB0_232:
	ds_read_b128 v[64:67], v81
	v_add_u32_e32 v100, s16, v95
	s_cmp_lt_i32 s5, 2
	s_mov_b64 s[14:15], -1
	s_cbranch_scc1 .LBB0_236
	s_cmp_eq_u32 s5, 2
	v_cmp_gt_i32_e32 vcc, s33, v100
	global_load_dwordx4 v[102:105], v[88:89], off
	global_load_dwordx4 v[106:109], v[90:91], off
	v_cndmask_b32_e32 v101, v189, v190, vcc
	v_and_b32_e32 v101, v101, v100
	v_lshrrev_b32_e32 v101, 2, v101
	v_cndmask_b32_e64 v101, v93, v101, s[46:47]
	v_lshlrev_b32_e32 v168, 2, v101
	v_lshl_add_u64 v[110:111], v[76:77], 0, v[168:169]
	v_lshl_add_u64 v[114:115], v[78:79], 0, v[168:169]
	global_load_dwordx4 v[110:113], v[110:111], off
	global_load_dwordx4 v[114:117], v[114:115], off
	s_waitcnt lgkmcnt(0)
	v_mov_b32_e32 v69, v67
	v_mov_b32_e32 v68, v66
	v_mov_b32_e32 v71, v65
	v_mov_b32_e32 v70, v64
	s_cbranch_scc0 .LBB0_235
	v_pk_mul_f32 v[70:71], v[64:65], v[64:65]
	v_pk_mul_f32 v[68:69], v[66:67], v[66:67]
	v_add_f32_e32 v70, v70, v71
	v_add_f32_e32 v68, v68, v70
	v_and_b32_e32 v70, 64, v182
	v_add_f32_e32 v68, v69, v68
	v_xor_b32_e32 v69, 1, v182
	v_add_u32_e32 v70, 64, v70
	v_cmp_lt_i32_e32 vcc, v69, v70
	s_nop 1
	v_cndmask_b32_e32 v69, v182, v69, vcc
	v_lshlrev_b32_e32 v69, 2, v69
	ds_bpermute_b32 v69, v69, v68
	s_waitcnt lgkmcnt(0)
	v_add_f32_e32 v68, v68, v69
	v_xor_b32_e32 v69, 2, v182
	v_cmp_lt_i32_e32 vcc, v69, v70
	s_nop 1
	v_cndmask_b32_e32 v69, v182, v69, vcc
	v_lshlrev_b32_e32 v69, 2, v69
	ds_bpermute_b32 v69, v69, v68
	s_waitcnt lgkmcnt(0)
	v_add_f32_e32 v68, v68, v69
	v_xor_b32_e32 v69, 4, v182
	v_cmp_lt_i32_e32 vcc, v69, v70
	s_nop 1
	v_cndmask_b32_e32 v69, v182, v69, vcc
	v_lshlrev_b32_e32 v69, 2, v69
	ds_bpermute_b32 v69, v69, v68
	s_waitcnt lgkmcnt(0)
	v_add_f32_e32 v68, v68, v69
	v_xor_b32_e32 v69, 8, v182
	v_cmp_lt_i32_e32 vcc, v69, v70
	s_nop 1
	v_cndmask_b32_e32 v69, v182, v69, vcc
	v_lshlrev_b32_e32 v69, 2, v69
	ds_bpermute_b32 v69, v69, v68
	s_waitcnt lgkmcnt(0)
	v_add_f32_e32 v68, v68, v69
	v_fmamk_f32 v68, v68, 0x3c800000, v172
	v_cmp_gt_f32_e32 vcc, s4, v68
	v_mul_f32_e32 v69, 0x4b800000, v68
	s_nop 0
	v_cndmask_b32_e32 v68, v68, v69, vcc
	v_rsq_f32_e32 v68, v68
	s_nop 0
	v_mul_f32_e32 v69, 0x45800000, v68
	v_cndmask_b32_e32 v92, v68, v69, vcc
	ds_read_b128 v[68:71], v83
	s_waitcnt lgkmcnt(0)
	v_pk_mul_f32 v[68:69], v[68:69], v[92:93] op_sel_hi:[1,0]
	v_pk_mul_f32 v[70:71], v[70:71], v[92:93] op_sel_hi:[1,0]
	s_waitcnt vmcnt(2)
	v_pk_mul_f32 v[68:69], v[106:107], v[68:69]
	v_pk_mul_f32 v[70:71], v[108:109], v[70:71]
	v_pk_mul_f32 v[106:107], v[66:67], v[92:93] op_sel_hi:[1,0]
	v_pk_mul_f32 v[108:109], v[64:65], v[92:93] op_sel_hi:[1,0]
	v_pk_mul_f32 v[104:105], v[104:105], v[106:107]
	v_pk_mul_f32 v[102:103], v[102:103], v[108:109]
	s_waitcnt vmcnt(0)
	v_pk_mul_f32 v[68:69], v[114:115], v[68:69]
	v_pk_mul_f32 v[70:71], v[116:117], v[70:71]
	v_cndmask_b32_e64 v107, v69, -v69, s[40:41]
	v_cndmask_b32_e64 v106, v68, -v68, s[40:41]
	v_cndmask_b32_e64 v69, v71, -v71, s[40:41]
	v_cndmask_b32_e64 v68, v70, -v70, s[40:41]
	v_pk_fma_f32 v[68:69], v[112:113], v[104:105], v[68:69]
	v_pk_fma_f32 v[70:71], v[110:111], v[102:103], v[106:107]

.LBB0_242:
	s_waitcnt lgkmcnt(0)
	v_pk_mul_f32 v[64:65], s[56:57], v[70:71]
	v_pk_mul_f32 v[66:67], s[56:57], v[68:69]
	v_cvt_pk_bf16_f32 v64, v64, v65
	v_cvt_pk_bf16_f32 v65, v66, v67
	v_ashrrev_i32_e32 v66, 31, v100
	v_mul_lo_u32 v68, s55, v100
	v_mul_lo_u32 v69, s54, v66
	v_mad_u64_u32 v[66:67], s[14:15], s54, v100, 0
	v_add3_u32 v67, v67, v69, v68
	v_lshl_add_u64 v[66:67], v[66:67], 1, v[86:87]
	global_store_dwordx2 v[66:67], v[64:65], off
	ds_read_b128 v[64:67], v81 offset:16640
	v_add_u32_e32 v101, 16, v100
	s_cmp_lt_i32 s5, 2
	s_mov_b64 s[14:15], -1
	s_cbranch_scc1 .LBB0_246
	s_cmp_eq_u32 s5, 2
	v_add_u32_e32 v111, 0x100, v99
	v_and_b32_e32 v111, 0x3f0, v111
	v_cmp_gt_i32_e32 vcc, s33, v101
	global_load_dwordx4 v[102:105], v[88:89], off
	global_load_dwordx4 v[106:109], v[90:91], off
	v_cndmask_b32_e32 v110, v189, v190, vcc
	v_and_b32_e32 v110, v110, v101
	v_lshrrev_b32_e32 v110, 2, v110
	v_cndmask_b32_e64 v110, v111, v110, s[46:47]
	v_lshlrev_b32_e32 v168, 2, v110
	v_lshl_add_u64 v[110:111], v[76:77], 0, v[168:169]
	v_lshl_add_u64 v[114:115], v[78:79], 0, v[168:169]
	global_load_dwordx4 v[110:113], v[110:111], off
	global_load_dwordx4 v[114:117], v[114:115], off
	s_waitcnt lgkmcnt(0)
	v_mov_b32_e32 v69, v67
	v_mov_b32_e32 v68, v66
	v_mov_b32_e32 v71, v65
	v_mov_b32_e32 v70, v64
	s_cbranch_scc0 .LBB0_245
	v_pk_mul_f32 v[70:71], v[64:65], v[64:65]
	v_pk_mul_f32 v[68:69], v[66:67], v[66:67]
	v_add_f32_e32 v70, v70, v71
	v_add_f32_e32 v68, v68, v70
	v_and_b32_e32 v70, 64, v182
	v_add_f32_e32 v68, v69, v68
	v_xor_b32_e32 v69, 1, v182
	v_add_u32_e32 v70, 64, v70
	v_cmp_lt_i32_e32 vcc, v69, v70
	v_cndmask_b32_e32 v69, v182, v69, vcc
	v_lshlrev_b32_e32 v69, 2, v69
	ds_bpermute_b32 v69, v69, v68
	s_waitcnt lgkmcnt(0)
	v_add_f32_e32 v68, v68, v69
	v_xor_b32_e32 v69, 2, v182
	v_cmp_lt_i32_e32 vcc, v69, v70
	s_nop 1
	v_cndmask_b32_e32 v69, v182, v69, vcc
	v_lshlrev_b32_e32 v69, 2, v69
	ds_bpermute_b32 v69, v69, v68
	s_waitcnt lgkmcnt(0)
	v_add_f32_e32 v68, v68, v69
	v_xor_b32_e32 v69, 4, v182
	v_cmp_lt_i32_e32 vcc, v69, v70
	s_nop 1
	v_cndmask_b32_e32 v69, v182, v69, vcc
	v_lshlrev_b32_e32 v69, 2, v69
	ds_bpermute_b32 v69, v69, v68
	s_waitcnt lgkmcnt(0)
	v_add_f32_e32 v68, v68, v69
	v_xor_b32_e32 v69, 8, v182
	v_cmp_lt_i32_e32 vcc, v69, v70
	s_nop 1
	v_cndmask_b32_e32 v69, v182, v69, vcc
	v_lshlrev_b32_e32 v69, 2, v69
	ds_bpermute_b32 v69, v69, v68
	s_waitcnt lgkmcnt(0)
	v_add_f32_e32 v68, v68, v69
	v_fmamk_f32 v68, v68, 0x3c800000, v172
	v_cmp_gt_f32_e32 vcc, s4, v68
	v_mul_f32_e32 v69, 0x4b800000, v68
	s_nop 0
	v_cndmask_b32_e32 v68, v68, v69, vcc
	v_rsq_f32_e32 v68, v68
	s_nop 0
	v_mul_f32_e32 v69, 0x45800000, v68
	v_cndmask_b32_e32 v92, v68, v69, vcc
	ds_read_b128 v[68:71], v83 offset:16640
	s_waitcnt lgkmcnt(0)
	v_pk_mul_f32 v[68:69], v[68:69], v[92:93] op_sel_hi:[1,0]
	v_pk_mul_f32 v[70:71], v[70:71], v[92:93] op_sel_hi:[1,0]
	s_waitcnt vmcnt(2)
	v_pk_mul_f32 v[68:69], v[106:107], v[68:69]
	v_pk_mul_f32 v[70:71], v[108:109], v[70:71]
	v_pk_mul_f32 v[106:107], v[66:67], v[92:93] op_sel_hi:[1,0]
	v_pk_mul_f32 v[108:109], v[64:65], v[92:93] op_sel_hi:[1,0]
	v_pk_mul_f32 v[104:105], v[104:105], v[106:107]
	v_pk_mul_f32 v[102:103], v[102:103], v[108:109]
	s_waitcnt vmcnt(0)
	v_pk_mul_f32 v[68:69], v[114:115], v[68:69]
	v_pk_mul_f32 v[70:71], v[116:117], v[70:71]
	v_cndmask_b32_e64 v107, v69, -v69, s[40:41]
	v_cndmask_b32_e64 v106, v68, -v68, s[40:41]
	v_cndmask_b32_e64 v69, v71, -v71, s[40:41]
	v_cndmask_b32_e64 v68, v70, -v70, s[40:41]
	v_pk_fma_f32 v[68:69], v[112:113], v[104:105], v[68:69]
	v_pk_fma_f32 v[70:71], v[110:111], v[102:103], v[106:107]

.LBB0_252:
	s_waitcnt lgkmcnt(0)
	v_pk_mul_f32 v[64:65], s[56:57], v[70:71]
	v_pk_mul_f32 v[66:67], s[56:57], v[68:69]
	v_cvt_pk_bf16_f32 v64, v64, v65
	v_cvt_pk_bf16_f32 v65, v66, v67
	v_ashrrev_i32_e32 v66, 31, v101
	v_mul_lo_u32 v68, s55, v101
	v_mul_lo_u32 v69, s54, v66
	v_mad_u64_u32 v[66:67], s[14:15], s54, v101, 0
	v_add3_u32 v67, v67, v69, v68
	v_lshl_add_u64 v[66:67], v[66:67], 1, v[86:87]
	global_store_dwordx2 v[66:67], v[64:65], off
	ds_read_b128 v[64:67], v81 offset:33280
	v_add_u32_e32 v101, 32, v100
	s_cmp_lt_i32 s5, 2
	s_mov_b64 s[14:15], -1
	s_cbranch_scc1 .LBB0_256
	s_cmp_eq_u32 s5, 2
	v_add_u32_e32 v111, 0x200, v99
	v_and_b32_e32 v111, 0x3f0, v111
	v_cmp_gt_i32_e32 vcc, s33, v101
	global_load_dwordx4 v[102:105], v[88:89], off
	global_load_dwordx4 v[106:109], v[90:91], off
	v_cndmask_b32_e32 v110, v189, v190, vcc
	v_and_b32_e32 v110, v110, v101
	v_lshrrev_b32_e32 v110, 2, v110
	v_cndmask_b32_e64 v110, v111, v110, s[46:47]
	v_lshlrev_b32_e32 v168, 2, v110
	v_lshl_add_u64 v[110:111], v[76:77], 0, v[168:169]
	v_lshl_add_u64 v[114:115], v[78:79], 0, v[168:169]
	global_load_dwordx4 v[110:113], v[110:111], off
	global_load_dwordx4 v[114:117], v[114:115], off
	s_waitcnt lgkmcnt(0)
	v_mov_b32_e32 v69, v67
	v_mov_b32_e32 v68, v66
	v_mov_b32_e32 v71, v65
	v_mov_b32_e32 v70, v64
	s_cbranch_scc0 .LBB0_255
	v_pk_mul_f32 v[70:71], v[64:65], v[64:65]
	v_pk_mul_f32 v[68:69], v[66:67], v[66:67]
	v_add_f32_e32 v70, v70, v71
	v_add_f32_e32 v68, v68, v70
	v_and_b32_e32 v70, 64, v182
	v_add_f32_e32 v68, v69, v68
	v_xor_b32_e32 v69, 1, v182
	v_add_u32_e32 v70, 64, v70
	v_cmp_lt_i32_e32 vcc, v69, v70
	v_cndmask_b32_e32 v69, v182, v69, vcc
	v_lshlrev_b32_e32 v69, 2, v69
	ds_bpermute_b32 v69, v69, v68
	s_waitcnt lgkmcnt(0)
	v_add_f32_e32 v68, v68, v69
	v_xor_b32_e32 v69, 2, v182
	v_cmp_lt_i32_e32 vcc, v69, v70
	s_nop 1
	v_cndmask_b32_e32 v69, v182, v69, vcc
	v_lshlrev_b32_e32 v69, 2, v69
	ds_bpermute_b32 v69, v69, v68
	s_waitcnt lgkmcnt(0)
	v_add_f32_e32 v68, v68, v69
	v_xor_b32_e32 v69, 4, v182
	v_cmp_lt_i32_e32 vcc, v69, v70
	s_nop 1
	v_cndmask_b32_e32 v69, v182, v69, vcc
	v_lshlrev_b32_e32 v69, 2, v69
	ds_bpermute_b32 v69, v69, v68
	s_waitcnt lgkmcnt(0)
	v_add_f32_e32 v68, v68, v69
	v_xor_b32_e32 v69, 8, v182
	v_cmp_lt_i32_e32 vcc, v69, v70
	s_nop 1
	v_cndmask_b32_e32 v69, v182, v69, vcc
	v_lshlrev_b32_e32 v69, 2, v69
	ds_bpermute_b32 v69, v69, v68
	s_waitcnt lgkmcnt(0)
	v_add_f32_e32 v68, v68, v69
	v_fmamk_f32 v68, v68, 0x3c800000, v172
	v_cmp_gt_f32_e32 vcc, s4, v68
	v_mul_f32_e32 v69, 0x4b800000, v68
	s_nop 0
	v_cndmask_b32_e32 v68, v68, v69, vcc
	v_rsq_f32_e32 v68, v68
	s_nop 0
	v_mul_f32_e32 v69, 0x45800000, v68
	v_cndmask_b32_e32 v92, v68, v69, vcc
	ds_read_b128 v[68:71], v83 offset:33280
	s_waitcnt lgkmcnt(0)
	v_pk_mul_f32 v[68:69], v[68:69], v[92:93] op_sel_hi:[1,0]
	v_pk_mul_f32 v[70:71], v[70:71], v[92:93] op_sel_hi:[1,0]
	s_waitcnt vmcnt(2)
	v_pk_mul_f32 v[68:69], v[106:107], v[68:69]
	v_pk_mul_f32 v[70:71], v[108:109], v[70:71]
	v_pk_mul_f32 v[106:107], v[66:67], v[92:93] op_sel_hi:[1,0]
	v_pk_mul_f32 v[108:109], v[64:65], v[92:93] op_sel_hi:[1,0]
	v_pk_mul_f32 v[104:105], v[104:105], v[106:107]
	v_pk_mul_f32 v[102:103], v[102:103], v[108:109]
	s_waitcnt vmcnt(0)
	v_pk_mul_f32 v[68:69], v[114:115], v[68:69]
	v_pk_mul_f32 v[70:71], v[116:117], v[70:71]
	v_cndmask_b32_e64 v107, v69, -v69, s[40:41]
	v_cndmask_b32_e64 v106, v68, -v68, s[40:41]
	v_cndmask_b32_e64 v69, v71, -v71, s[40:41]
	v_cndmask_b32_e64 v68, v70, -v70, s[40:41]
	v_pk_fma_f32 v[68:69], v[112:113], v[104:105], v[68:69]
	v_pk_fma_f32 v[70:71], v[110:111], v[102:103], v[106:107]

.LBB0_262:
	s_waitcnt lgkmcnt(0)
	v_pk_mul_f32 v[64:65], s[56:57], v[70:71]
	v_pk_mul_f32 v[66:67], s[56:57], v[68:69]
	v_cvt_pk_bf16_f32 v64, v64, v65
	v_cvt_pk_bf16_f32 v65, v66, v67
	v_ashrrev_i32_e32 v66, 31, v101
	v_mul_lo_u32 v68, s55, v101
	v_mul_lo_u32 v69, s54, v66
	v_mad_u64_u32 v[66:67], s[14:15], s54, v101, 0
	v_add3_u32 v67, v67, v69, v68
	v_lshl_add_u64 v[66:67], v[66:67], 1, v[86:87]
	global_store_dwordx2 v[66:67], v[64:65], off
	ds_read_b128 v[64:67], v81 offset:49920
	v_add_u32_e32 v100, 48, v100
	s_cmp_lt_i32 s5, 2
	s_mov_b64 s[14:15], -1
	s_cbranch_scc1 .LBB0_266
	s_cmp_eq_u32 s5, 2
	v_add_u32_e32 v110, 0x300, v99
	v_and_b32_e32 v110, 0x3f0, v110
	v_cmp_gt_i32_e32 vcc, s33, v100
	global_load_dwordx4 v[102:105], v[88:89], off
	global_load_dwordx4 v[106:109], v[90:91], off
	v_cndmask_b32_e32 v101, v189, v190, vcc
	v_and_b32_e32 v101, v101, v100
	v_lshrrev_b32_e32 v101, 2, v101
	v_cndmask_b32_e64 v101, v110, v101, s[46:47]
	v_lshlrev_b32_e32 v168, 2, v101
	v_lshl_add_u64 v[110:111], v[76:77], 0, v[168:169]
	v_lshl_add_u64 v[114:115], v[78:79], 0, v[168:169]
	global_load_dwordx4 v[110:113], v[110:111], off
	global_load_dwordx4 v[114:117], v[114:115], off
	s_waitcnt lgkmcnt(0)
	v_mov_b32_e32 v69, v67
	v_mov_b32_e32 v68, v66
	v_mov_b32_e32 v71, v65
	v_mov_b32_e32 v70, v64
	s_cbranch_scc0 .LBB0_265
	v_pk_mul_f32 v[70:71], v[64:65], v[64:65]
	v_pk_mul_f32 v[68:69], v[66:67], v[66:67]
	v_add_f32_e32 v70, v70, v71
	v_add_f32_e32 v68, v68, v70
	v_and_b32_e32 v70, 64, v182
	v_add_f32_e32 v68, v69, v68
	v_xor_b32_e32 v69, 1, v182
	v_add_u32_e32 v70, 64, v70
	v_cmp_lt_i32_e32 vcc, v69, v70
	v_cndmask_b32_e32 v69, v182, v69, vcc
	v_lshlrev_b32_e32 v69, 2, v69
	ds_bpermute_b32 v69, v69, v68
	s_waitcnt lgkmcnt(0)
	v_add_f32_e32 v68, v68, v69
	v_xor_b32_e32 v69, 2, v182
	v_cmp_lt_i32_e32 vcc, v69, v70
	s_nop 1
	v_cndmask_b32_e32 v69, v182, v69, vcc
	v_lshlrev_b32_e32 v69, 2, v69
	ds_bpermute_b32 v69, v69, v68
	s_waitcnt lgkmcnt(0)
	v_add_f32_e32 v68, v68, v69
	v_xor_b32_e32 v69, 4, v182
	v_cmp_lt_i32_e32 vcc, v69, v70
	s_nop 1
	v_cndmask_b32_e32 v69, v182, v69, vcc
	v_lshlrev_b32_e32 v69, 2, v69
	ds_bpermute_b32 v69, v69, v68
	s_waitcnt lgkmcnt(0)
	v_add_f32_e32 v68, v68, v69
	v_xor_b32_e32 v69, 8, v182
	v_cmp_lt_i32_e32 vcc, v69, v70
	s_nop 1
	v_cndmask_b32_e32 v69, v182, v69, vcc
	v_lshlrev_b32_e32 v69, 2, v69
	ds_bpermute_b32 v69, v69, v68
	s_waitcnt lgkmcnt(0)
	v_add_f32_e32 v68, v68, v69
	v_fmamk_f32 v68, v68, 0x3c800000, v172
	v_cmp_gt_f32_e32 vcc, s4, v68
	v_mul_f32_e32 v69, 0x4b800000, v68
	s_nop 0
	v_cndmask_b32_e32 v68, v68, v69, vcc
	v_rsq_f32_e32 v68, v68
	s_nop 0
	v_mul_f32_e32 v69, 0x45800000, v68
	v_cndmask_b32_e32 v92, v68, v69, vcc
	ds_read_b128 v[68:71], v83 offset:49920
	s_waitcnt lgkmcnt(0)
	v_pk_mul_f32 v[68:69], v[68:69], v[92:93] op_sel_hi:[1,0]
	v_pk_mul_f32 v[70:71], v[70:71], v[92:93] op_sel_hi:[1,0]
	s_waitcnt vmcnt(2)
	v_pk_mul_f32 v[68:69], v[106:107], v[68:69]
	v_pk_mul_f32 v[70:71], v[108:109], v[70:71]
	v_pk_mul_f32 v[106:107], v[66:67], v[92:93] op_sel_hi:[1,0]
	v_pk_mul_f32 v[108:109], v[64:65], v[92:93] op_sel_hi:[1,0]
	v_pk_mul_f32 v[104:105], v[104:105], v[106:107]
	v_pk_mul_f32 v[102:103], v[102:103], v[108:109]
	s_waitcnt vmcnt(0)
	v_pk_mul_f32 v[68:69], v[114:115], v[68:69]
	v_pk_mul_f32 v[70:71], v[116:117], v[70:71]
	v_cndmask_b32_e64 v107, v69, -v69, s[40:41]
	v_cndmask_b32_e64 v106, v68, -v68, s[40:41]
	v_cndmask_b32_e64 v69, v71, -v71, s[40:41]
	v_cndmask_b32_e64 v68, v70, -v70, s[40:41]
	v_pk_fma_f32 v[68:69], v[112:113], v[104:105], v[68:69]
	v_pk_fma_f32 v[70:71], v[110:111], v[102:103], v[106:107]

.LBB0_289:
	ds_read_b128 v[64:67], v89
	v_add_u32_e32 v90, s16, v95
	s_cmp_lt_i32 s5, 2
	s_mov_b64 s[14:15], -1
	s_cbranch_scc1 .LBB0_293
	s_cmp_eq_u32 s5, 2
	v_cmp_gt_i32_e32 vcc, s33, v90
	global_load_dwordx4 v[96:99], v[82:83], off
	global_load_dwordx4 v[100:103], v[80:81], off
	v_cndmask_b32_e32 v91, v189, v190, vcc
	v_and_b32_e32 v91, v91, v90
	v_lshrrev_b32_e32 v91, 2, v91
	v_cndmask_b32_e64 v91, v93, v91, s[46:47]
	v_lshlrev_b32_e32 v168, 2, v91
	v_lshl_add_u64 v[104:105], v[76:77], 0, v[168:169]
	v_lshl_add_u64 v[108:109], v[78:79], 0, v[168:169]
	global_load_dwordx4 v[104:107], v[104:105], off
	global_load_dwordx4 v[108:111], v[108:109], off
	s_waitcnt lgkmcnt(0)
	v_mov_b32_e32 v69, v67
	v_mov_b32_e32 v68, v66
	v_mov_b32_e32 v71, v65
	v_mov_b32_e32 v70, v64
	s_cbranch_scc0 .LBB0_292
	v_pk_mul_f32 v[70:71], v[64:65], v[64:65]
	v_pk_mul_f32 v[68:69], v[66:67], v[66:67]
	v_add_f32_e32 v70, v70, v71
	v_add_f32_e32 v68, v68, v70
	v_and_b32_e32 v70, 64, v182
	v_add_f32_e32 v68, v69, v68
	v_xor_b32_e32 v69, 1, v182
	v_add_u32_e32 v70, 64, v70
	v_cmp_lt_i32_e32 vcc, v69, v70
	s_nop 1
	v_cndmask_b32_e32 v69, v182, v69, vcc
	v_lshlrev_b32_e32 v69, 2, v69
	ds_bpermute_b32 v69, v69, v68
	s_waitcnt lgkmcnt(0)
	v_add_f32_e32 v68, v68, v69
	v_xor_b32_e32 v69, 2, v182
	v_cmp_lt_i32_e32 vcc, v69, v70
	s_nop 1
	v_cndmask_b32_e32 v69, v182, v69, vcc
	v_lshlrev_b32_e32 v69, 2, v69
	ds_bpermute_b32 v69, v69, v68
	s_waitcnt lgkmcnt(0)
	v_add_f32_e32 v68, v68, v69
	v_xor_b32_e32 v69, 4, v182
	v_cmp_lt_i32_e32 vcc, v69, v70
	s_nop 1
	v_cndmask_b32_e32 v69, v182, v69, vcc
	v_lshlrev_b32_e32 v69, 2, v69
	ds_bpermute_b32 v69, v69, v68
	s_waitcnt lgkmcnt(0)
	v_add_f32_e32 v68, v68, v69
	v_xor_b32_e32 v69, 8, v182
	v_cmp_lt_i32_e32 vcc, v69, v70
	s_nop 1
	v_cndmask_b32_e32 v69, v182, v69, vcc
	v_lshlrev_b32_e32 v69, 2, v69
	ds_bpermute_b32 v69, v69, v68
	s_waitcnt lgkmcnt(0)
	v_add_f32_e32 v68, v68, v69
	v_fmamk_f32 v68, v68, 0x3c800000, v172
	v_cmp_gt_f32_e32 vcc, s4, v68
	v_mul_f32_e32 v69, 0x4b800000, v68
	s_nop 0
	v_cndmask_b32_e32 v68, v68, v69, vcc
	v_rsq_f32_e32 v68, v68
	s_nop 0
	v_mul_f32_e32 v69, 0x45800000, v68
	v_cndmask_b32_e32 v86, v68, v69, vcc
	ds_read_b128 v[68:71], v88
	s_waitcnt lgkmcnt(0)
	v_pk_mul_f32 v[68:69], v[68:69], v[86:87] op_sel_hi:[1,0]
	v_pk_mul_f32 v[70:71], v[70:71], v[86:87] op_sel_hi:[1,0]
	s_waitcnt vmcnt(2)
	v_pk_mul_f32 v[68:69], v[100:101], v[68:69]
	v_pk_mul_f32 v[70:71], v[102:103], v[70:71]
	v_pk_mul_f32 v[100:101], v[66:67], v[86:87] op_sel_hi:[1,0]
	v_pk_mul_f32 v[102:103], v[64:65], v[86:87] op_sel_hi:[1,0]
	v_pk_mul_f32 v[98:99], v[98:99], v[100:101]
	v_pk_mul_f32 v[96:97], v[96:97], v[102:103]
	s_waitcnt vmcnt(0)
	v_pk_mul_f32 v[68:69], v[108:109], v[68:69]
	v_pk_mul_f32 v[70:71], v[110:111], v[70:71]
	v_cndmask_b32_e64 v101, v69, -v69, s[40:41]
	v_cndmask_b32_e64 v100, v68, -v68, s[40:41]
	v_cndmask_b32_e64 v69, v71, -v71, s[40:41]
	v_cndmask_b32_e64 v68, v70, -v70, s[40:41]
	v_pk_fma_f32 v[68:69], v[106:107], v[98:99], v[68:69]
	v_pk_fma_f32 v[70:71], v[104:105], v[96:97], v[100:101]

.LBB0_299:
	s_waitcnt lgkmcnt(0)
	v_pk_mul_f32 v[64:65], s[86:87], v[70:71]
	v_pk_mul_f32 v[66:67], s[86:87], v[68:69]
	v_cvt_pk_bf16_f32 v64, v64, v65
	v_cvt_pk_bf16_f32 v65, v66, v67
	v_ashrrev_i32_e32 v66, 31, v90
	v_mul_lo_u32 v68, s85, v90
	v_mul_lo_u32 v69, s84, v66
	v_mad_u64_u32 v[66:67], s[14:15], s84, v90, 0
	v_add3_u32 v67, v67, v69, v68
	v_lshl_add_u64 v[66:67], v[66:67], 1, v[84:85]
	global_store_dwordx2 v[66:67], v[64:65], off
	ds_read_b128 v[64:67], v89 offset:16640
	v_add_u32_e32 v91, 16, v90
	s_cmp_lt_i32 s5, 2
	s_mov_b64 s[14:15], -1
	s_cbranch_scc1 .LBB0_303
	s_cmp_eq_u32 s5, 2
	v_add_u32_e32 v104, 0x100, v94
	v_and_b32_e32 v104, 0x3f0, v104
	v_cmp_gt_i32_e32 vcc, s33, v91
	global_load_dwordx4 v[96:99], v[82:83], off
	global_load_dwordx4 v[100:103], v[80:81], off
	v_cndmask_b32_e32 v92, v189, v190, vcc
	v_and_b32_e32 v92, v92, v91
	v_lshrrev_b32_e32 v92, 2, v92
	v_cndmask_b32_e64 v92, v104, v92, s[46:47]
	v_lshlrev_b32_e32 v168, 2, v92
	v_lshl_add_u64 v[104:105], v[76:77], 0, v[168:169]
	v_lshl_add_u64 v[108:109], v[78:79], 0, v[168:169]
	global_load_dwordx4 v[104:107], v[104:105], off
	global_load_dwordx4 v[108:111], v[108:109], off
	s_waitcnt lgkmcnt(0)
	v_mov_b32_e32 v69, v67
	v_mov_b32_e32 v68, v66
	v_mov_b32_e32 v71, v65
	v_mov_b32_e32 v70, v64
	s_cbranch_scc0 .LBB0_302
	v_pk_mul_f32 v[70:71], v[64:65], v[64:65]
	v_pk_mul_f32 v[68:69], v[66:67], v[66:67]
	v_add_f32_e32 v70, v70, v71
	v_add_f32_e32 v68, v68, v70
	v_and_b32_e32 v70, 64, v182
	v_add_f32_e32 v68, v69, v68
	v_xor_b32_e32 v69, 1, v182
	v_add_u32_e32 v70, 64, v70
	v_cmp_lt_i32_e32 vcc, v69, v70
	v_cndmask_b32_e32 v69, v182, v69, vcc
	v_lshlrev_b32_e32 v69, 2, v69
	ds_bpermute_b32 v69, v69, v68
	s_waitcnt lgkmcnt(0)
	v_add_f32_e32 v68, v68, v69
	v_xor_b32_e32 v69, 2, v182
	v_cmp_lt_i32_e32 vcc, v69, v70
	s_nop 1
	v_cndmask_b32_e32 v69, v182, v69, vcc
	v_lshlrev_b32_e32 v69, 2, v69
	ds_bpermute_b32 v69, v69, v68
	s_waitcnt lgkmcnt(0)
	v_add_f32_e32 v68, v68, v69
	v_xor_b32_e32 v69, 4, v182
	v_cmp_lt_i32_e32 vcc, v69, v70
	s_nop 1
	v_cndmask_b32_e32 v69, v182, v69, vcc
	v_lshlrev_b32_e32 v69, 2, v69
	ds_bpermute_b32 v69, v69, v68
	s_waitcnt lgkmcnt(0)
	v_add_f32_e32 v68, v68, v69
	v_xor_b32_e32 v69, 8, v182
	v_cmp_lt_i32_e32 vcc, v69, v70
	s_nop 1
	v_cndmask_b32_e32 v69, v182, v69, vcc
	v_lshlrev_b32_e32 v69, 2, v69
	ds_bpermute_b32 v69, v69, v68
	s_waitcnt lgkmcnt(0)
	v_add_f32_e32 v68, v68, v69
	v_fmamk_f32 v68, v68, 0x3c800000, v172
	v_cmp_gt_f32_e32 vcc, s4, v68
	v_mul_f32_e32 v69, 0x4b800000, v68
	s_nop 0
	v_cndmask_b32_e32 v68, v68, v69, vcc
	v_rsq_f32_e32 v68, v68
	s_nop 0
	v_mul_f32_e32 v69, 0x45800000, v68
	v_cndmask_b32_e32 v86, v68, v69, vcc
	ds_read_b128 v[68:71], v88 offset:16640
	s_waitcnt lgkmcnt(0)
	v_pk_mul_f32 v[68:69], v[68:69], v[86:87] op_sel_hi:[1,0]
	v_pk_mul_f32 v[70:71], v[70:71], v[86:87] op_sel_hi:[1,0]
	s_waitcnt vmcnt(2)
	v_pk_mul_f32 v[68:69], v[100:101], v[68:69]
	v_pk_mul_f32 v[70:71], v[102:103], v[70:71]
	v_pk_mul_f32 v[100:101], v[66:67], v[86:87] op_sel_hi:[1,0]
	v_pk_mul_f32 v[102:103], v[64:65], v[86:87] op_sel_hi:[1,0]
	v_pk_mul_f32 v[98:99], v[98:99], v[100:101]
	v_pk_mul_f32 v[96:97], v[96:97], v[102:103]
	s_waitcnt vmcnt(0)
	v_pk_mul_f32 v[68:69], v[108:109], v[68:69]
	v_pk_mul_f32 v[70:71], v[110:111], v[70:71]
	v_cndmask_b32_e64 v101, v69, -v69, s[40:41]
	v_cndmask_b32_e64 v100, v68, -v68, s[40:41]
	v_cndmask_b32_e64 v69, v71, -v71, s[40:41]
	v_cndmask_b32_e64 v68, v70, -v70, s[40:41]
	v_pk_fma_f32 v[68:69], v[106:107], v[98:99], v[68:69]
	v_pk_fma_f32 v[70:71], v[104:105], v[96:97], v[100:101]

.LBB0_309:
	s_waitcnt lgkmcnt(0)
	v_pk_mul_f32 v[64:65], s[86:87], v[70:71]
	v_pk_mul_f32 v[66:67], s[86:87], v[68:69]
	v_cvt_pk_bf16_f32 v64, v64, v65
	v_cvt_pk_bf16_f32 v65, v66, v67
	v_ashrrev_i32_e32 v66, 31, v91
	v_mul_lo_u32 v68, s85, v91
	v_mul_lo_u32 v69, s84, v66
	v_mad_u64_u32 v[66:67], s[14:15], s84, v91, 0
	v_add3_u32 v67, v67, v69, v68
	v_lshl_add_u64 v[66:67], v[66:67], 1, v[84:85]
	global_store_dwordx2 v[66:67], v[64:65], off
	ds_read_b128 v[64:67], v89 offset:33280
	v_add_u32_e32 v91, 32, v90
	s_cmp_lt_i32 s5, 2
	s_mov_b64 s[14:15], -1
	s_cbranch_scc1 .LBB0_313
	s_cmp_eq_u32 s5, 2
	v_add_u32_e32 v104, 0x200, v94
	v_and_b32_e32 v104, 0x3f0, v104
	v_cmp_gt_i32_e32 vcc, s33, v91
	global_load_dwordx4 v[96:99], v[82:83], off
	global_load_dwordx4 v[100:103], v[80:81], off
	v_cndmask_b32_e32 v92, v189, v190, vcc
	v_and_b32_e32 v92, v92, v91
	v_lshrrev_b32_e32 v92, 2, v92
	v_cndmask_b32_e64 v92, v104, v92, s[46:47]
	v_lshlrev_b32_e32 v168, 2, v92
	v_lshl_add_u64 v[104:105], v[76:77], 0, v[168:169]
	v_lshl_add_u64 v[108:109], v[78:79], 0, v[168:169]
	global_load_dwordx4 v[104:107], v[104:105], off
	global_load_dwordx4 v[108:111], v[108:109], off
	s_waitcnt lgkmcnt(0)
	v_mov_b32_e32 v69, v67
	v_mov_b32_e32 v68, v66
	v_mov_b32_e32 v71, v65
	v_mov_b32_e32 v70, v64
	s_cbranch_scc0 .LBB0_312
	v_pk_mul_f32 v[70:71], v[64:65], v[64:65]
	v_pk_mul_f32 v[68:69], v[66:67], v[66:67]
	v_add_f32_e32 v70, v70, v71
	v_add_f32_e32 v68, v68, v70
	v_and_b32_e32 v70, 64, v182
	v_add_f32_e32 v68, v69, v68
	v_xor_b32_e32 v69, 1, v182
	v_add_u32_e32 v70, 64, v70
	v_cmp_lt_i32_e32 vcc, v69, v70
	v_cndmask_b32_e32 v69, v182, v69, vcc
	v_lshlrev_b32_e32 v69, 2, v69
	ds_bpermute_b32 v69, v69, v68
	s_waitcnt lgkmcnt(0)
	v_add_f32_e32 v68, v68, v69
	v_xor_b32_e32 v69, 2, v182
	v_cmp_lt_i32_e32 vcc, v69, v70
	s_nop 1
	v_cndmask_b32_e32 v69, v182, v69, vcc
	v_lshlrev_b32_e32 v69, 2, v69
	ds_bpermute_b32 v69, v69, v68
	s_waitcnt lgkmcnt(0)
	v_add_f32_e32 v68, v68, v69
	v_xor_b32_e32 v69, 4, v182
	v_cmp_lt_i32_e32 vcc, v69, v70
	s_nop 1
	v_cndmask_b32_e32 v69, v182, v69, vcc
	v_lshlrev_b32_e32 v69, 2, v69
	ds_bpermute_b32 v69, v69, v68
	s_waitcnt lgkmcnt(0)
	v_add_f32_e32 v68, v68, v69
	v_xor_b32_e32 v69, 8, v182
	v_cmp_lt_i32_e32 vcc, v69, v70
	s_nop 1
	v_cndmask_b32_e32 v69, v182, v69, vcc
	v_lshlrev_b32_e32 v69, 2, v69
	ds_bpermute_b32 v69, v69, v68
	s_waitcnt lgkmcnt(0)
	v_add_f32_e32 v68, v68, v69
	v_fmamk_f32 v68, v68, 0x3c800000, v172
	v_cmp_gt_f32_e32 vcc, s4, v68
	v_mul_f32_e32 v69, 0x4b800000, v68
	s_nop 0
	v_cndmask_b32_e32 v68, v68, v69, vcc
	v_rsq_f32_e32 v68, v68
	s_nop 0
	v_mul_f32_e32 v69, 0x45800000, v68
	v_cndmask_b32_e32 v86, v68, v69, vcc
	ds_read_b128 v[68:71], v88 offset:33280
	s_waitcnt lgkmcnt(0)
	v_pk_mul_f32 v[68:69], v[68:69], v[86:87] op_sel_hi:[1,0]
	v_pk_mul_f32 v[70:71], v[70:71], v[86:87] op_sel_hi:[1,0]
	s_waitcnt vmcnt(2)
	v_pk_mul_f32 v[68:69], v[100:101], v[68:69]
	v_pk_mul_f32 v[70:71], v[102:103], v[70:71]
	v_pk_mul_f32 v[100:101], v[66:67], v[86:87] op_sel_hi:[1,0]
	v_pk_mul_f32 v[102:103], v[64:65], v[86:87] op_sel_hi:[1,0]
	v_pk_mul_f32 v[98:99], v[98:99], v[100:101]
	v_pk_mul_f32 v[96:97], v[96:97], v[102:103]
	s_waitcnt vmcnt(0)
	v_pk_mul_f32 v[68:69], v[108:109], v[68:69]
	v_pk_mul_f32 v[70:71], v[110:111], v[70:71]
	v_cndmask_b32_e64 v101, v69, -v69, s[40:41]
	v_cndmask_b32_e64 v100, v68, -v68, s[40:41]
	v_cndmask_b32_e64 v69, v71, -v71, s[40:41]
	v_cndmask_b32_e64 v68, v70, -v70, s[40:41]
	v_pk_fma_f32 v[68:69], v[106:107], v[98:99], v[68:69]
	v_pk_fma_f32 v[70:71], v[104:105], v[96:97], v[100:101]

.LBB0_319:
	s_waitcnt lgkmcnt(0)
	v_pk_mul_f32 v[64:65], s[86:87], v[70:71]
	v_pk_mul_f32 v[66:67], s[86:87], v[68:69]
	v_cvt_pk_bf16_f32 v64, v64, v65
	v_cvt_pk_bf16_f32 v65, v66, v67
	v_ashrrev_i32_e32 v66, 31, v91
	v_mul_lo_u32 v68, s85, v91
	v_mul_lo_u32 v69, s84, v66
	v_mad_u64_u32 v[66:67], s[14:15], s84, v91, 0
	v_add3_u32 v67, v67, v69, v68
	v_lshl_add_u64 v[66:67], v[66:67], 1, v[84:85]
	global_store_dwordx2 v[66:67], v[64:65], off
	ds_read_b128 v[64:67], v89 offset:49920
	v_add_u32_e32 v90, 48, v90
	s_cmp_lt_i32 s5, 2
	s_mov_b64 s[14:15], -1
	s_cbranch_scc1 .LBB0_323
	s_cmp_eq_u32 s5, 2
	v_add_u32_e32 v92, 0x300, v94
	v_and_b32_e32 v92, 0x3f0, v92
	v_cmp_gt_i32_e32 vcc, s33, v90
	global_load_dwordx4 v[96:99], v[82:83], off
	global_load_dwordx4 v[100:103], v[80:81], off
	v_cndmask_b32_e32 v91, v189, v190, vcc
	v_and_b32_e32 v91, v91, v90
	v_lshrrev_b32_e32 v91, 2, v91
	v_cndmask_b32_e64 v91, v92, v91, s[46:47]
	v_lshlrev_b32_e32 v168, 2, v91
	v_lshl_add_u64 v[104:105], v[76:77], 0, v[168:169]
	v_lshl_add_u64 v[108:109], v[78:79], 0, v[168:169]
	global_load_dwordx4 v[104:107], v[104:105], off
	global_load_dwordx4 v[108:111], v[108:109], off
	s_waitcnt lgkmcnt(0)
	v_mov_b32_e32 v69, v67
	v_mov_b32_e32 v68, v66
	v_mov_b32_e32 v71, v65
	v_mov_b32_e32 v70, v64
	s_cbranch_scc0 .LBB0_322
	v_pk_mul_f32 v[70:71], v[64:65], v[64:65]
	v_pk_mul_f32 v[68:69], v[66:67], v[66:67]
	v_add_f32_e32 v70, v70, v71
	v_add_f32_e32 v68, v68, v70
	v_and_b32_e32 v70, 64, v182
	v_add_f32_e32 v68, v69, v68
	v_xor_b32_e32 v69, 1, v182
	v_add_u32_e32 v70, 64, v70
	v_cmp_lt_i32_e32 vcc, v69, v70
	v_cndmask_b32_e32 v69, v182, v69, vcc
	v_lshlrev_b32_e32 v69, 2, v69
	ds_bpermute_b32 v69, v69, v68
	s_waitcnt lgkmcnt(0)
	v_add_f32_e32 v68, v68, v69
	v_xor_b32_e32 v69, 2, v182
	v_cmp_lt_i32_e32 vcc, v69, v70
	s_nop 1
	v_cndmask_b32_e32 v69, v182, v69, vcc
	v_lshlrev_b32_e32 v69, 2, v69
	ds_bpermute_b32 v69, v69, v68
	s_waitcnt lgkmcnt(0)
	v_add_f32_e32 v68, v68, v69
	v_xor_b32_e32 v69, 4, v182
	v_cmp_lt_i32_e32 vcc, v69, v70
	s_nop 1
	v_cndmask_b32_e32 v69, v182, v69, vcc
	v_lshlrev_b32_e32 v69, 2, v69
	ds_bpermute_b32 v69, v69, v68
	s_waitcnt lgkmcnt(0)
	v_add_f32_e32 v68, v68, v69
	v_xor_b32_e32 v69, 8, v182
	v_cmp_lt_i32_e32 vcc, v69, v70
	s_nop 1
	v_cndmask_b32_e32 v69, v182, v69, vcc
	v_lshlrev_b32_e32 v69, 2, v69
	ds_bpermute_b32 v69, v69, v68
	s_waitcnt lgkmcnt(0)
	v_add_f32_e32 v68, v68, v69
	v_fmamk_f32 v68, v68, 0x3c800000, v172
	v_cmp_gt_f32_e32 vcc, s4, v68
	v_mul_f32_e32 v69, 0x4b800000, v68
	s_nop 0
	v_cndmask_b32_e32 v68, v68, v69, vcc
	v_rsq_f32_e32 v68, v68
	s_nop 0
	v_mul_f32_e32 v69, 0x45800000, v68
	v_cndmask_b32_e32 v86, v68, v69, vcc
	ds_read_b128 v[68:71], v88 offset:49920
	s_waitcnt lgkmcnt(0)
	v_pk_mul_f32 v[68:69], v[68:69], v[86:87] op_sel_hi:[1,0]
	v_pk_mul_f32 v[70:71], v[70:71], v[86:87] op_sel_hi:[1,0]
	s_waitcnt vmcnt(2)
	v_pk_mul_f32 v[68:69], v[100:101], v[68:69]
	v_pk_mul_f32 v[70:71], v[102:103], v[70:71]
	v_pk_mul_f32 v[100:101], v[66:67], v[86:87] op_sel_hi:[1,0]
	v_pk_mul_f32 v[102:103], v[64:65], v[86:87] op_sel_hi:[1,0]
	v_pk_mul_f32 v[98:99], v[98:99], v[100:101]
	v_pk_mul_f32 v[96:97], v[96:97], v[102:103]
	s_waitcnt vmcnt(0)
	v_pk_mul_f32 v[68:69], v[108:109], v[68:69]
	v_pk_mul_f32 v[70:71], v[110:111], v[70:71]
	v_cndmask_b32_e64 v101, v69, -v69, s[40:41]
	v_cndmask_b32_e64 v100, v68, -v68, s[40:41]
	v_cndmask_b32_e64 v69, v71, -v71, s[40:41]
	v_cndmask_b32_e64 v68, v70, -v70, s[40:41]
	v_pk_fma_f32 v[68:69], v[106:107], v[98:99], v[68:69]
	v_pk_fma_f32 v[70:71], v[104:105], v[96:97], v[100:101]

.LBB0_347:
	ds_read_b128 v[0:3], v17
	v_add_u32_e32 v36, s16, v31
	v_add_u32_e32 v37, 0x80, v36
	s_cmp_lt_i32 s5, 2
	s_mov_b64 s[14:15], -1
	s_cbranch_scc1 .LBB0_351
	s_cmp_eq_u32 s5, 2
	v_cmp_gt_i32_e32 vcc, s33, v37
	global_load_dwordx4 v[38:41], v[24:25], off
	global_load_dwordx4 v[42:45], v[26:27], off
	v_cndmask_b32_e32 v46, v189, v190, vcc
	v_and_b32_e32 v46, v46, v37
	v_lshrrev_b32_e32 v46, 2, v46
	v_cndmask_b32_e64 v46, v29, v46, s[46:47]
	v_lshlrev_b32_e32 v168, 2, v46
	v_lshl_add_u64 v[46:47], v[12:13], 0, v[168:169]
	v_lshl_add_u64 v[50:51], v[14:15], 0, v[168:169]
	global_load_dwordx4 v[46:49], v[46:47], off
	global_load_dwordx4 v[50:53], v[50:51], off
	s_waitcnt lgkmcnt(0)
	v_mov_b32_e32 v5, v3
	v_mov_b32_e32 v4, v2
	v_mov_b32_e32 v7, v1
	v_mov_b32_e32 v6, v0
	s_cbranch_scc0 .LBB0_350
	v_pk_mul_f32 v[6:7], v[0:1], v[0:1]
	v_pk_mul_f32 v[4:5], v[2:3], v[2:3]
	v_add_f32_e32 v6, v6, v7
	v_add_f32_e32 v4, v4, v6
	v_and_b32_e32 v6, 64, v182
	v_add_f32_e32 v4, v5, v4
	v_xor_b32_e32 v5, 1, v182
	v_add_u32_e32 v6, 64, v6
	v_cmp_lt_i32_e32 vcc, v5, v6
	s_nop 1
	v_cndmask_b32_e32 v5, v182, v5, vcc
	v_lshlrev_b32_e32 v5, 2, v5
	ds_bpermute_b32 v5, v5, v4
	s_waitcnt lgkmcnt(0)
	v_add_f32_e32 v4, v4, v5
	v_xor_b32_e32 v5, 2, v182
	v_cmp_lt_i32_e32 vcc, v5, v6
	s_nop 1
	v_cndmask_b32_e32 v5, v182, v5, vcc
	v_lshlrev_b32_e32 v5, 2, v5
	ds_bpermute_b32 v5, v5, v4
	s_waitcnt lgkmcnt(0)
	v_add_f32_e32 v4, v4, v5
	v_xor_b32_e32 v5, 4, v182
	v_cmp_lt_i32_e32 vcc, v5, v6
	s_nop 1
	v_cndmask_b32_e32 v5, v182, v5, vcc
	v_lshlrev_b32_e32 v5, 2, v5
	ds_bpermute_b32 v5, v5, v4
	s_waitcnt lgkmcnt(0)
	v_add_f32_e32 v4, v4, v5
	v_xor_b32_e32 v5, 8, v182
	v_cmp_lt_i32_e32 vcc, v5, v6
	s_nop 1
	v_cndmask_b32_e32 v5, v182, v5, vcc
	v_lshlrev_b32_e32 v5, 2, v5
	ds_bpermute_b32 v5, v5, v4
	s_waitcnt lgkmcnt(0)
	v_add_f32_e32 v4, v4, v5
	v_fmamk_f32 v4, v4, 0x3c800000, v172
	v_cmp_gt_f32_e32 vcc, s4, v4
	v_mul_f32_e32 v5, 0x4b800000, v4
	s_nop 0
	v_cndmask_b32_e32 v4, v4, v5, vcc
	v_rsq_f32_e32 v4, v4
	s_nop 0
	v_mul_f32_e32 v5, 0x45800000, v4
	v_cndmask_b32_e32 v28, v4, v5, vcc
	ds_read_b128 v[4:7], v19
	s_waitcnt lgkmcnt(0)
	v_pk_mul_f32 v[4:5], v[4:5], v[28:29] op_sel_hi:[1,0]
	v_pk_mul_f32 v[6:7], v[6:7], v[28:29] op_sel_hi:[1,0]
	s_waitcnt vmcnt(2)
	v_pk_mul_f32 v[4:5], v[42:43], v[4:5]
	v_pk_mul_f32 v[6:7], v[44:45], v[6:7]
	v_pk_mul_f32 v[42:43], v[2:3], v[28:29] op_sel_hi:[1,0]
	v_pk_mul_f32 v[44:45], v[0:1], v[28:29] op_sel_hi:[1,0]
	v_pk_mul_f32 v[40:41], v[40:41], v[42:43]
	v_pk_mul_f32 v[38:39], v[38:39], v[44:45]
	s_waitcnt vmcnt(0)
	v_pk_mul_f32 v[4:5], v[50:51], v[4:5]
	v_pk_mul_f32 v[6:7], v[52:53], v[6:7]
	v_cndmask_b32_e64 v43, v5, -v5, s[40:41]
	v_cndmask_b32_e64 v42, v4, -v4, s[40:41]
	v_cndmask_b32_e64 v5, v7, -v7, s[40:41]
	v_cndmask_b32_e64 v4, v6, -v6, s[40:41]
	v_pk_fma_f32 v[4:5], v[48:49], v[40:41], v[4:5]
	v_pk_fma_f32 v[6:7], v[46:47], v[38:39], v[42:43]

.LBB0_357:
	s_waitcnt lgkmcnt(0)
	v_pk_mul_f32 v[0:1], s[84:85], v[6:7]
	v_pk_mul_f32 v[2:3], s[84:85], v[4:5]
	v_cvt_pk_bf16_f32 v0, v0, v1
	v_cvt_pk_bf16_f32 v1, v2, v3
	v_ashrrev_i32_e32 v2, 31, v37
	v_mul_lo_u32 v4, s91, v37
	v_mul_lo_u32 v5, s90, v2
	v_mad_u64_u32 v[2:3], s[14:15], s90, v37, 0
	v_add3_u32 v3, v3, v5, v4
	v_lshl_add_u64 v[2:3], v[2:3], 1, v[22:23]
	global_store_dwordx2 v[2:3], v[0:1], off
	ds_read_b128 v[0:3], v17 offset:16640
	v_add_u32_e32 v37, 0x90, v36
	s_cmp_lt_i32 s5, 2
	s_mov_b64 s[14:15], -1
	s_cbranch_scc1 .LBB0_361
	s_cmp_eq_u32 s5, 2
	v_add_u32_e32 v47, 0x100, v35
	v_and_b32_e32 v47, 0x3f0, v47
	v_cmp_gt_i32_e32 vcc, s33, v37
	global_load_dwordx4 v[38:41], v[24:25], off
	global_load_dwordx4 v[42:45], v[26:27], off
	v_cndmask_b32_e32 v46, v189, v190, vcc
	v_and_b32_e32 v46, v46, v37
	v_lshrrev_b32_e32 v46, 2, v46
	v_cndmask_b32_e64 v46, v47, v46, s[46:47]
	v_lshlrev_b32_e32 v168, 2, v46
	v_lshl_add_u64 v[46:47], v[12:13], 0, v[168:169]
	v_lshl_add_u64 v[50:51], v[14:15], 0, v[168:169]
	global_load_dwordx4 v[46:49], v[46:47], off
	global_load_dwordx4 v[50:53], v[50:51], off
	s_waitcnt lgkmcnt(0)
	v_mov_b32_e32 v5, v3
	v_mov_b32_e32 v4, v2
	v_mov_b32_e32 v7, v1
	v_mov_b32_e32 v6, v0
	s_cbranch_scc0 .LBB0_360
	v_pk_mul_f32 v[6:7], v[0:1], v[0:1]
	v_pk_mul_f32 v[4:5], v[2:3], v[2:3]
	v_add_f32_e32 v6, v6, v7
	v_add_f32_e32 v4, v4, v6
	v_and_b32_e32 v6, 64, v182
	v_add_f32_e32 v4, v5, v4
	v_xor_b32_e32 v5, 1, v182
	v_add_u32_e32 v6, 64, v6
	v_cmp_lt_i32_e32 vcc, v5, v6
	v_cndmask_b32_e32 v5, v182, v5, vcc
	v_lshlrev_b32_e32 v5, 2, v5
	ds_bpermute_b32 v5, v5, v4
	s_waitcnt lgkmcnt(0)
	v_add_f32_e32 v4, v4, v5
	v_xor_b32_e32 v5, 2, v182
	v_cmp_lt_i32_e32 vcc, v5, v6
	s_nop 1
	v_cndmask_b32_e32 v5, v182, v5, vcc
	v_lshlrev_b32_e32 v5, 2, v5
	ds_bpermute_b32 v5, v5, v4
	s_waitcnt lgkmcnt(0)
	v_add_f32_e32 v4, v4, v5
	v_xor_b32_e32 v5, 4, v182
	v_cmp_lt_i32_e32 vcc, v5, v6
	s_nop 1
	v_cndmask_b32_e32 v5, v182, v5, vcc
	v_lshlrev_b32_e32 v5, 2, v5
	ds_bpermute_b32 v5, v5, v4
	s_waitcnt lgkmcnt(0)
	v_add_f32_e32 v4, v4, v5
	v_xor_b32_e32 v5, 8, v182
	v_cmp_lt_i32_e32 vcc, v5, v6
	s_nop 1
	v_cndmask_b32_e32 v5, v182, v5, vcc
	v_lshlrev_b32_e32 v5, 2, v5
	ds_bpermute_b32 v5, v5, v4
	s_waitcnt lgkmcnt(0)
	v_add_f32_e32 v4, v4, v5
	v_fmamk_f32 v4, v4, 0x3c800000, v172
	v_cmp_gt_f32_e32 vcc, s4, v4
	v_mul_f32_e32 v5, 0x4b800000, v4
	s_nop 0
	v_cndmask_b32_e32 v4, v4, v5, vcc
	v_rsq_f32_e32 v4, v4
	s_nop 0
	v_mul_f32_e32 v5, 0x45800000, v4
	v_cndmask_b32_e32 v28, v4, v5, vcc
	ds_read_b128 v[4:7], v19 offset:16640
	s_waitcnt lgkmcnt(0)
	v_pk_mul_f32 v[4:5], v[4:5], v[28:29] op_sel_hi:[1,0]
	v_pk_mul_f32 v[6:7], v[6:7], v[28:29] op_sel_hi:[1,0]
	s_waitcnt vmcnt(2)
	v_pk_mul_f32 v[4:5], v[42:43], v[4:5]
	v_pk_mul_f32 v[6:7], v[44:45], v[6:7]
	v_pk_mul_f32 v[42:43], v[2:3], v[28:29] op_sel_hi:[1,0]
	v_pk_mul_f32 v[44:45], v[0:1], v[28:29] op_sel_hi:[1,0]
	v_pk_mul_f32 v[40:41], v[40:41], v[42:43]
	v_pk_mul_f32 v[38:39], v[38:39], v[44:45]
	s_waitcnt vmcnt(0)
	v_pk_mul_f32 v[4:5], v[50:51], v[4:5]
	v_pk_mul_f32 v[6:7], v[52:53], v[6:7]
	v_cndmask_b32_e64 v43, v5, -v5, s[40:41]
	v_cndmask_b32_e64 v42, v4, -v4, s[40:41]
	v_cndmask_b32_e64 v5, v7, -v7, s[40:41]
	v_cndmask_b32_e64 v4, v6, -v6, s[40:41]
	v_pk_fma_f32 v[4:5], v[48:49], v[40:41], v[4:5]
	v_pk_fma_f32 v[6:7], v[46:47], v[38:39], v[42:43]

.LBB0_367:
	s_waitcnt lgkmcnt(0)
	v_pk_mul_f32 v[0:1], s[84:85], v[6:7]
	v_pk_mul_f32 v[2:3], s[84:85], v[4:5]
	v_cvt_pk_bf16_f32 v0, v0, v1
	v_cvt_pk_bf16_f32 v1, v2, v3
	v_ashrrev_i32_e32 v2, 31, v37
	v_mul_lo_u32 v4, s91, v37
	v_mul_lo_u32 v5, s90, v2
	v_mad_u64_u32 v[2:3], s[14:15], s90, v37, 0
	v_add3_u32 v3, v3, v5, v4
	v_lshl_add_u64 v[2:3], v[2:3], 1, v[22:23]
	global_store_dwordx2 v[2:3], v[0:1], off
	ds_read_b128 v[0:3], v17 offset:33280
	v_add_u32_e32 v37, 0xa0, v36
	s_cmp_lt_i32 s5, 2
	s_mov_b64 s[14:15], -1
	s_cbranch_scc1 .LBB0_371
	s_cmp_eq_u32 s5, 2
	v_add_u32_e32 v47, 0x200, v35
	v_and_b32_e32 v47, 0x3f0, v47
	v_cmp_gt_i32_e32 vcc, s33, v37
	global_load_dwordx4 v[38:41], v[24:25], off
	global_load_dwordx4 v[42:45], v[26:27], off
	v_cndmask_b32_e32 v46, v189, v190, vcc
	v_and_b32_e32 v46, v46, v37
	v_lshrrev_b32_e32 v46, 2, v46
	v_cndmask_b32_e64 v46, v47, v46, s[46:47]
	v_lshlrev_b32_e32 v168, 2, v46
	v_lshl_add_u64 v[46:47], v[12:13], 0, v[168:169]
	v_lshl_add_u64 v[50:51], v[14:15], 0, v[168:169]
	global_load_dwordx4 v[46:49], v[46:47], off
	global_load_dwordx4 v[50:53], v[50:51], off
	s_waitcnt lgkmcnt(0)
	v_mov_b32_e32 v5, v3
	v_mov_b32_e32 v4, v2
	v_mov_b32_e32 v7, v1
	v_mov_b32_e32 v6, v0
	s_cbranch_scc0 .LBB0_370
	v_pk_mul_f32 v[6:7], v[0:1], v[0:1]
	v_pk_mul_f32 v[4:5], v[2:3], v[2:3]
	v_add_f32_e32 v6, v6, v7
	v_add_f32_e32 v4, v4, v6
	v_and_b32_e32 v6, 64, v182
	v_add_f32_e32 v4, v5, v4
	v_xor_b32_e32 v5, 1, v182
	v_add_u32_e32 v6, 64, v6
	v_cmp_lt_i32_e32 vcc, v5, v6
	v_cndmask_b32_e32 v5, v182, v5, vcc
	v_lshlrev_b32_e32 v5, 2, v5
	ds_bpermute_b32 v5, v5, v4
	s_waitcnt lgkmcnt(0)
	v_add_f32_e32 v4, v4, v5
	v_xor_b32_e32 v5, 2, v182
	v_cmp_lt_i32_e32 vcc, v5, v6
	s_nop 1
	v_cndmask_b32_e32 v5, v182, v5, vcc
	v_lshlrev_b32_e32 v5, 2, v5
	ds_bpermute_b32 v5, v5, v4
	s_waitcnt lgkmcnt(0)
	v_add_f32_e32 v4, v4, v5
	v_xor_b32_e32 v5, 4, v182
	v_cmp_lt_i32_e32 vcc, v5, v6
	s_nop 1
	v_cndmask_b32_e32 v5, v182, v5, vcc
	v_lshlrev_b32_e32 v5, 2, v5
	ds_bpermute_b32 v5, v5, v4
	s_waitcnt lgkmcnt(0)
	v_add_f32_e32 v4, v4, v5
	v_xor_b32_e32 v5, 8, v182
	v_cmp_lt_i32_e32 vcc, v5, v6
	s_nop 1
	v_cndmask_b32_e32 v5, v182, v5, vcc
	v_lshlrev_b32_e32 v5, 2, v5
	ds_bpermute_b32 v5, v5, v4
	s_waitcnt lgkmcnt(0)
	v_add_f32_e32 v4, v4, v5
	v_fmamk_f32 v4, v4, 0x3c800000, v172
	v_cmp_gt_f32_e32 vcc, s4, v4
	v_mul_f32_e32 v5, 0x4b800000, v4
	s_nop 0
	v_cndmask_b32_e32 v4, v4, v5, vcc
	v_rsq_f32_e32 v4, v4
	s_nop 0
	v_mul_f32_e32 v5, 0x45800000, v4
	v_cndmask_b32_e32 v28, v4, v5, vcc
	ds_read_b128 v[4:7], v19 offset:33280
	s_waitcnt lgkmcnt(0)
	v_pk_mul_f32 v[4:5], v[4:5], v[28:29] op_sel_hi:[1,0]
	v_pk_mul_f32 v[6:7], v[6:7], v[28:29] op_sel_hi:[1,0]
	s_waitcnt vmcnt(2)
	v_pk_mul_f32 v[4:5], v[42:43], v[4:5]
	v_pk_mul_f32 v[6:7], v[44:45], v[6:7]
	v_pk_mul_f32 v[42:43], v[2:3], v[28:29] op_sel_hi:[1,0]
	v_pk_mul_f32 v[44:45], v[0:1], v[28:29] op_sel_hi:[1,0]
	v_pk_mul_f32 v[40:41], v[40:41], v[42:43]
	v_pk_mul_f32 v[38:39], v[38:39], v[44:45]
	s_waitcnt vmcnt(0)
	v_pk_mul_f32 v[4:5], v[50:51], v[4:5]
	v_pk_mul_f32 v[6:7], v[52:53], v[6:7]
	v_cndmask_b32_e64 v43, v5, -v5, s[40:41]
	v_cndmask_b32_e64 v42, v4, -v4, s[40:41]
	v_cndmask_b32_e64 v5, v7, -v7, s[40:41]
	v_cndmask_b32_e64 v4, v6, -v6, s[40:41]
	v_pk_fma_f32 v[4:5], v[48:49], v[40:41], v[4:5]
	v_pk_fma_f32 v[6:7], v[46:47], v[38:39], v[42:43]

.LBB0_377:
	s_waitcnt lgkmcnt(0)
	v_pk_mul_f32 v[0:1], s[84:85], v[6:7]
	v_pk_mul_f32 v[2:3], s[84:85], v[4:5]
	v_cvt_pk_bf16_f32 v0, v0, v1
	v_cvt_pk_bf16_f32 v1, v2, v3
	v_ashrrev_i32_e32 v2, 31, v37
	v_mul_lo_u32 v4, s91, v37
	v_mul_lo_u32 v5, s90, v2
	v_mad_u64_u32 v[2:3], s[14:15], s90, v37, 0
	v_add3_u32 v3, v3, v5, v4
	v_lshl_add_u64 v[2:3], v[2:3], 1, v[22:23]
	global_store_dwordx2 v[2:3], v[0:1], off
	ds_read_b128 v[0:3], v17 offset:49920
	v_add_u32_e32 v36, 0xb0, v36
	s_cmp_lt_i32 s5, 2
	s_mov_b64 s[14:15], -1
	s_cbranch_scc1 .LBB0_381
	s_cmp_eq_u32 s5, 2
	v_add_u32_e32 v46, 0x300, v35
	v_and_b32_e32 v46, 0x3f0, v46
	v_cmp_gt_i32_e32 vcc, s33, v36
	global_load_dwordx4 v[38:41], v[24:25], off
	global_load_dwordx4 v[42:45], v[26:27], off
	v_cndmask_b32_e32 v37, v189, v190, vcc
	v_and_b32_e32 v37, v37, v36
	v_lshrrev_b32_e32 v37, 2, v37
	v_cndmask_b32_e64 v37, v46, v37, s[46:47]
	v_lshlrev_b32_e32 v168, 2, v37
	v_lshl_add_u64 v[46:47], v[12:13], 0, v[168:169]
	v_lshl_add_u64 v[50:51], v[14:15], 0, v[168:169]
	global_load_dwordx4 v[46:49], v[46:47], off
	global_load_dwordx4 v[50:53], v[50:51], off
	s_waitcnt lgkmcnt(0)
	v_mov_b32_e32 v5, v3
	v_mov_b32_e32 v4, v2
	v_mov_b32_e32 v7, v1
	v_mov_b32_e32 v6, v0
	s_cbranch_scc0 .LBB0_380
	v_pk_mul_f32 v[6:7], v[0:1], v[0:1]
	v_pk_mul_f32 v[4:5], v[2:3], v[2:3]
	v_add_f32_e32 v6, v6, v7
	v_add_f32_e32 v4, v4, v6
	v_and_b32_e32 v6, 64, v182
	v_add_f32_e32 v4, v5, v4
	v_xor_b32_e32 v5, 1, v182
	v_add_u32_e32 v6, 64, v6
	v_cmp_lt_i32_e32 vcc, v5, v6
	v_cndmask_b32_e32 v5, v182, v5, vcc
	v_lshlrev_b32_e32 v5, 2, v5
	ds_bpermute_b32 v5, v5, v4
	s_waitcnt lgkmcnt(0)
	v_add_f32_e32 v4, v4, v5
	v_xor_b32_e32 v5, 2, v182
	v_cmp_lt_i32_e32 vcc, v5, v6
	s_nop 1
	v_cndmask_b32_e32 v5, v182, v5, vcc
	v_lshlrev_b32_e32 v5, 2, v5
	ds_bpermute_b32 v5, v5, v4
	s_waitcnt lgkmcnt(0)
	v_add_f32_e32 v4, v4, v5
	v_xor_b32_e32 v5, 4, v182
	v_cmp_lt_i32_e32 vcc, v5, v6
	s_nop 1
	v_cndmask_b32_e32 v5, v182, v5, vcc
	v_lshlrev_b32_e32 v5, 2, v5
	ds_bpermute_b32 v5, v5, v4
	s_waitcnt lgkmcnt(0)
	v_add_f32_e32 v4, v4, v5
	v_xor_b32_e32 v5, 8, v182
	v_cmp_lt_i32_e32 vcc, v5, v6
	s_nop 1
	v_cndmask_b32_e32 v5, v182, v5, vcc
	v_lshlrev_b32_e32 v5, 2, v5
	ds_bpermute_b32 v5, v5, v4
	s_waitcnt lgkmcnt(0)
	v_add_f32_e32 v4, v4, v5
	v_fmamk_f32 v4, v4, 0x3c800000, v172
	v_cmp_gt_f32_e32 vcc, s4, v4
	v_mul_f32_e32 v5, 0x4b800000, v4
	s_nop 0
	v_cndmask_b32_e32 v4, v4, v5, vcc
	v_rsq_f32_e32 v4, v4
	s_nop 0
	v_mul_f32_e32 v5, 0x45800000, v4
	v_cndmask_b32_e32 v28, v4, v5, vcc
	ds_read_b128 v[4:7], v19 offset:49920
	s_waitcnt lgkmcnt(0)
	v_pk_mul_f32 v[4:5], v[4:5], v[28:29] op_sel_hi:[1,0]
	v_pk_mul_f32 v[6:7], v[6:7], v[28:29] op_sel_hi:[1,0]
	s_waitcnt vmcnt(2)
	v_pk_mul_f32 v[4:5], v[42:43], v[4:5]
	v_pk_mul_f32 v[6:7], v[44:45], v[6:7]
	v_pk_mul_f32 v[42:43], v[2:3], v[28:29] op_sel_hi:[1,0]
	v_pk_mul_f32 v[44:45], v[0:1], v[28:29] op_sel_hi:[1,0]
	v_pk_mul_f32 v[40:41], v[40:41], v[42:43]
	v_pk_mul_f32 v[38:39], v[38:39], v[44:45]
	s_waitcnt vmcnt(0)
	v_pk_mul_f32 v[4:5], v[50:51], v[4:5]
	v_pk_mul_f32 v[6:7], v[52:53], v[6:7]
	v_cndmask_b32_e64 v43, v5, -v5, s[40:41]
	v_cndmask_b32_e64 v42, v4, -v4, s[40:41]
	v_cndmask_b32_e64 v5, v7, -v7, s[40:41]
	v_cndmask_b32_e64 v4, v6, -v6, s[40:41]
	v_pk_fma_f32 v[4:5], v[48:49], v[40:41], v[4:5]
	v_pk_fma_f32 v[6:7], v[46:47], v[38:39], v[42:43]

.LBB0_405:
	ds_read_b128 v[0:3], v25
	v_add_u32_e32 v26, s16, v31
	v_add_u32_e32 v27, 0x80, v26
	s_cmp_lt_i32 s5, 2
	s_mov_b64 s[14:15], -1
	s_cbranch_scc1 .LBB0_409
	s_cmp_eq_u32 s5, 2
	v_cmp_gt_i32_e32 vcc, s33, v27
	global_load_dwordx4 v[32:35], v[18:19], off
	global_load_dwordx4 v[36:39], v[16:17], off
	v_cndmask_b32_e32 v28, v189, v190, vcc
	v_and_b32_e32 v28, v28, v27
	v_lshrrev_b32_e32 v28, 2, v28
	v_cndmask_b32_e64 v28, v29, v28, s[46:47]
	v_lshlrev_b32_e32 v168, 2, v28
	v_lshl_add_u64 v[40:41], v[12:13], 0, v[168:169]
	v_lshl_add_u64 v[44:45], v[14:15], 0, v[168:169]
	global_load_dwordx4 v[40:43], v[40:41], off
	global_load_dwordx4 v[44:47], v[44:45], off
	s_waitcnt lgkmcnt(0)
	v_mov_b32_e32 v5, v3
	v_mov_b32_e32 v4, v2
	v_mov_b32_e32 v7, v1
	v_mov_b32_e32 v6, v0
	s_cbranch_scc0 .LBB0_408
	v_pk_mul_f32 v[6:7], v[0:1], v[0:1]
	v_pk_mul_f32 v[4:5], v[2:3], v[2:3]
	v_add_f32_e32 v6, v6, v7
	v_add_f32_e32 v4, v4, v6
	v_and_b32_e32 v6, 64, v182
	v_add_f32_e32 v4, v5, v4
	v_xor_b32_e32 v5, 1, v182
	v_add_u32_e32 v6, 64, v6
	v_cmp_lt_i32_e32 vcc, v5, v6
	s_nop 1
	v_cndmask_b32_e32 v5, v182, v5, vcc
	v_lshlrev_b32_e32 v5, 2, v5
	ds_bpermute_b32 v5, v5, v4
	s_waitcnt lgkmcnt(0)
	v_add_f32_e32 v4, v4, v5
	v_xor_b32_e32 v5, 2, v182
	v_cmp_lt_i32_e32 vcc, v5, v6
	s_nop 1
	v_cndmask_b32_e32 v5, v182, v5, vcc
	v_lshlrev_b32_e32 v5, 2, v5
	ds_bpermute_b32 v5, v5, v4
	s_waitcnt lgkmcnt(0)
	v_add_f32_e32 v4, v4, v5
	v_xor_b32_e32 v5, 4, v182
	v_cmp_lt_i32_e32 vcc, v5, v6
	s_nop 1
	v_cndmask_b32_e32 v5, v182, v5, vcc
	v_lshlrev_b32_e32 v5, 2, v5
	ds_bpermute_b32 v5, v5, v4
	s_waitcnt lgkmcnt(0)
	v_add_f32_e32 v4, v4, v5
	v_xor_b32_e32 v5, 8, v182
	v_cmp_lt_i32_e32 vcc, v5, v6
	s_nop 1
	v_cndmask_b32_e32 v5, v182, v5, vcc
	v_lshlrev_b32_e32 v5, 2, v5
	ds_bpermute_b32 v5, v5, v4
	s_waitcnt lgkmcnt(0)
	v_add_f32_e32 v4, v4, v5
	v_fmamk_f32 v4, v4, 0x3c800000, v172
	v_cmp_gt_f32_e32 vcc, s4, v4
	v_mul_f32_e32 v5, 0x4b800000, v4
	s_nop 0
	v_cndmask_b32_e32 v4, v4, v5, vcc
	v_rsq_f32_e32 v4, v4
	s_nop 0
	v_mul_f32_e32 v5, 0x45800000, v4
	v_cndmask_b32_e32 v22, v4, v5, vcc
	ds_read_b128 v[4:7], v24
	s_waitcnt lgkmcnt(0)
	v_pk_mul_f32 v[4:5], v[4:5], v[22:23] op_sel_hi:[1,0]
	v_pk_mul_f32 v[6:7], v[6:7], v[22:23] op_sel_hi:[1,0]
	s_waitcnt vmcnt(2)
	v_pk_mul_f32 v[4:5], v[36:37], v[4:5]
	v_pk_mul_f32 v[6:7], v[38:39], v[6:7]
	v_pk_mul_f32 v[36:37], v[2:3], v[22:23] op_sel_hi:[1,0]
	v_pk_mul_f32 v[38:39], v[0:1], v[22:23] op_sel_hi:[1,0]
	v_pk_mul_f32 v[34:35], v[34:35], v[36:37]
	v_pk_mul_f32 v[32:33], v[32:33], v[38:39]
	s_waitcnt vmcnt(0)
	v_pk_mul_f32 v[4:5], v[44:45], v[4:5]
	v_pk_mul_f32 v[6:7], v[46:47], v[6:7]
	v_cndmask_b32_e64 v37, v5, -v5, s[40:41]
	v_cndmask_b32_e64 v36, v4, -v4, s[40:41]
	v_cndmask_b32_e64 v5, v7, -v7, s[40:41]
	v_cndmask_b32_e64 v4, v6, -v6, s[40:41]
	v_pk_fma_f32 v[4:5], v[42:43], v[34:35], v[4:5]
	v_pk_fma_f32 v[6:7], v[40:41], v[32:33], v[36:37]

.LBB0_415:
	s_waitcnt lgkmcnt(0)
	v_pk_mul_f32 v[0:1], s[84:85], v[6:7]
	v_pk_mul_f32 v[2:3], s[84:85], v[4:5]
	v_cvt_pk_bf16_f32 v0, v0, v1
	v_cvt_pk_bf16_f32 v1, v2, v3
	v_ashrrev_i32_e32 v2, 31, v27
	v_mul_lo_u32 v4, s55, v27
	v_mul_lo_u32 v5, s54, v2
	v_mad_u64_u32 v[2:3], s[14:15], s54, v27, 0
	v_add3_u32 v3, v3, v5, v4
	v_lshl_add_u64 v[2:3], v[2:3], 1, v[20:21]
	global_store_dwordx2 v[2:3], v[0:1], off
	ds_read_b128 v[0:3], v25 offset:16640
	v_add_u32_e32 v27, 0x90, v26
	s_cmp_lt_i32 s5, 2
	s_mov_b64 s[14:15], -1
	s_cbranch_scc1 .LBB0_419
	s_cmp_eq_u32 s5, 2
	v_add_u32_e32 v40, 0x100, v30
	v_and_b32_e32 v40, 0x3f0, v40
	v_cmp_gt_i32_e32 vcc, s33, v27
	global_load_dwordx4 v[32:35], v[18:19], off
	global_load_dwordx4 v[36:39], v[16:17], off
	v_cndmask_b32_e32 v28, v189, v190, vcc
	v_and_b32_e32 v28, v28, v27
	v_lshrrev_b32_e32 v28, 2, v28
	v_cndmask_b32_e64 v28, v40, v28, s[46:47]
	v_lshlrev_b32_e32 v168, 2, v28
	v_lshl_add_u64 v[40:41], v[12:13], 0, v[168:169]
	v_lshl_add_u64 v[44:45], v[14:15], 0, v[168:169]
	global_load_dwordx4 v[40:43], v[40:41], off
	global_load_dwordx4 v[44:47], v[44:45], off
	s_waitcnt lgkmcnt(0)
	v_mov_b32_e32 v5, v3
	v_mov_b32_e32 v4, v2
	v_mov_b32_e32 v7, v1
	v_mov_b32_e32 v6, v0
	s_cbranch_scc0 .LBB0_418
	v_pk_mul_f32 v[6:7], v[0:1], v[0:1]
	v_pk_mul_f32 v[4:5], v[2:3], v[2:3]
	v_add_f32_e32 v6, v6, v7
	v_add_f32_e32 v4, v4, v6
	v_and_b32_e32 v6, 64, v182
	v_add_f32_e32 v4, v5, v4
	v_xor_b32_e32 v5, 1, v182
	v_add_u32_e32 v6, 64, v6
	v_cmp_lt_i32_e32 vcc, v5, v6
	v_cndmask_b32_e32 v5, v182, v5, vcc
	v_lshlrev_b32_e32 v5, 2, v5
	ds_bpermute_b32 v5, v5, v4
	s_waitcnt lgkmcnt(0)
	v_add_f32_e32 v4, v4, v5
	v_xor_b32_e32 v5, 2, v182
	v_cmp_lt_i32_e32 vcc, v5, v6
	s_nop 1
	v_cndmask_b32_e32 v5, v182, v5, vcc
	v_lshlrev_b32_e32 v5, 2, v5
	ds_bpermute_b32 v5, v5, v4
	s_waitcnt lgkmcnt(0)
	v_add_f32_e32 v4, v4, v5
	v_xor_b32_e32 v5, 4, v182
	v_cmp_lt_i32_e32 vcc, v5, v6
	s_nop 1
	v_cndmask_b32_e32 v5, v182, v5, vcc
	v_lshlrev_b32_e32 v5, 2, v5
	ds_bpermute_b32 v5, v5, v4
	s_waitcnt lgkmcnt(0)
	v_add_f32_e32 v4, v4, v5
	v_xor_b32_e32 v5, 8, v182
	v_cmp_lt_i32_e32 vcc, v5, v6
	s_nop 1
	v_cndmask_b32_e32 v5, v182, v5, vcc
	v_lshlrev_b32_e32 v5, 2, v5
	ds_bpermute_b32 v5, v5, v4
	s_waitcnt lgkmcnt(0)
	v_add_f32_e32 v4, v4, v5
	v_fmamk_f32 v4, v4, 0x3c800000, v172
	v_cmp_gt_f32_e32 vcc, s4, v4
	v_mul_f32_e32 v5, 0x4b800000, v4
	s_nop 0
	v_cndmask_b32_e32 v4, v4, v5, vcc
	v_rsq_f32_e32 v4, v4
	s_nop 0
	v_mul_f32_e32 v5, 0x45800000, v4
	v_cndmask_b32_e32 v22, v4, v5, vcc
	ds_read_b128 v[4:7], v24 offset:16640
	s_waitcnt lgkmcnt(0)
	v_pk_mul_f32 v[4:5], v[4:5], v[22:23] op_sel_hi:[1,0]
	v_pk_mul_f32 v[6:7], v[6:7], v[22:23] op_sel_hi:[1,0]
	s_waitcnt vmcnt(2)
	v_pk_mul_f32 v[4:5], v[36:37], v[4:5]
	v_pk_mul_f32 v[6:7], v[38:39], v[6:7]
	v_pk_mul_f32 v[36:37], v[2:3], v[22:23] op_sel_hi:[1,0]
	v_pk_mul_f32 v[38:39], v[0:1], v[22:23] op_sel_hi:[1,0]
	v_pk_mul_f32 v[34:35], v[34:35], v[36:37]
	v_pk_mul_f32 v[32:33], v[32:33], v[38:39]
	s_waitcnt vmcnt(0)
	v_pk_mul_f32 v[4:5], v[44:45], v[4:5]
	v_pk_mul_f32 v[6:7], v[46:47], v[6:7]
	v_cndmask_b32_e64 v37, v5, -v5, s[40:41]
	v_cndmask_b32_e64 v36, v4, -v4, s[40:41]
	v_cndmask_b32_e64 v5, v7, -v7, s[40:41]
	v_cndmask_b32_e64 v4, v6, -v6, s[40:41]
	v_pk_fma_f32 v[4:5], v[42:43], v[34:35], v[4:5]
	v_pk_fma_f32 v[6:7], v[40:41], v[32:33], v[36:37]

.LBB0_425:
	s_waitcnt lgkmcnt(0)
	v_pk_mul_f32 v[0:1], s[84:85], v[6:7]
	v_pk_mul_f32 v[2:3], s[84:85], v[4:5]
	v_cvt_pk_bf16_f32 v0, v0, v1
	v_cvt_pk_bf16_f32 v1, v2, v3
	v_ashrrev_i32_e32 v2, 31, v27
	v_mul_lo_u32 v4, s55, v27
	v_mul_lo_u32 v5, s54, v2
	v_mad_u64_u32 v[2:3], s[14:15], s54, v27, 0
	v_add3_u32 v3, v3, v5, v4
	v_lshl_add_u64 v[2:3], v[2:3], 1, v[20:21]
	global_store_dwordx2 v[2:3], v[0:1], off
	ds_read_b128 v[0:3], v25 offset:33280
	v_add_u32_e32 v27, 0xa0, v26
	s_cmp_lt_i32 s5, 2
	s_mov_b64 s[14:15], -1
	s_cbranch_scc1 .LBB0_429
	s_cmp_eq_u32 s5, 2
	v_add_u32_e32 v40, 0x200, v30
	v_and_b32_e32 v40, 0x3f0, v40
	v_cmp_gt_i32_e32 vcc, s33, v27
	global_load_dwordx4 v[32:35], v[18:19], off
	global_load_dwordx4 v[36:39], v[16:17], off
	v_cndmask_b32_e32 v28, v189, v190, vcc
	v_and_b32_e32 v28, v28, v27
	v_lshrrev_b32_e32 v28, 2, v28
	v_cndmask_b32_e64 v28, v40, v28, s[46:47]
	v_lshlrev_b32_e32 v168, 2, v28
	v_lshl_add_u64 v[40:41], v[12:13], 0, v[168:169]
	v_lshl_add_u64 v[44:45], v[14:15], 0, v[168:169]
	global_load_dwordx4 v[40:43], v[40:41], off
	global_load_dwordx4 v[44:47], v[44:45], off
	s_waitcnt lgkmcnt(0)
	v_mov_b32_e32 v5, v3
	v_mov_b32_e32 v4, v2
	v_mov_b32_e32 v7, v1
	v_mov_b32_e32 v6, v0
	s_cbranch_scc0 .LBB0_428
	v_pk_mul_f32 v[6:7], v[0:1], v[0:1]
	v_pk_mul_f32 v[4:5], v[2:3], v[2:3]
	v_add_f32_e32 v6, v6, v7
	v_add_f32_e32 v4, v4, v6
	v_and_b32_e32 v6, 64, v182
	v_add_f32_e32 v4, v5, v4
	v_xor_b32_e32 v5, 1, v182
	v_add_u32_e32 v6, 64, v6
	v_cmp_lt_i32_e32 vcc, v5, v6
	v_cndmask_b32_e32 v5, v182, v5, vcc
	v_lshlrev_b32_e32 v5, 2, v5
	ds_bpermute_b32 v5, v5, v4
	s_waitcnt lgkmcnt(0)
	v_add_f32_e32 v4, v4, v5
	v_xor_b32_e32 v5, 2, v182
	v_cmp_lt_i32_e32 vcc, v5, v6
	s_nop 1
	v_cndmask_b32_e32 v5, v182, v5, vcc
	v_lshlrev_b32_e32 v5, 2, v5
	ds_bpermute_b32 v5, v5, v4
	s_waitcnt lgkmcnt(0)
	v_add_f32_e32 v4, v4, v5
	v_xor_b32_e32 v5, 4, v182
	v_cmp_lt_i32_e32 vcc, v5, v6
	s_nop 1
	v_cndmask_b32_e32 v5, v182, v5, vcc
	v_lshlrev_b32_e32 v5, 2, v5
	ds_bpermute_b32 v5, v5, v4
	s_waitcnt lgkmcnt(0)
	v_add_f32_e32 v4, v4, v5
	v_xor_b32_e32 v5, 8, v182
	v_cmp_lt_i32_e32 vcc, v5, v6
	s_nop 1
	v_cndmask_b32_e32 v5, v182, v5, vcc
	v_lshlrev_b32_e32 v5, 2, v5
	ds_bpermute_b32 v5, v5, v4
	s_waitcnt lgkmcnt(0)
	v_add_f32_e32 v4, v4, v5
	v_fmamk_f32 v4, v4, 0x3c800000, v172
	v_cmp_gt_f32_e32 vcc, s4, v4
	v_mul_f32_e32 v5, 0x4b800000, v4
	s_nop 0
	v_cndmask_b32_e32 v4, v4, v5, vcc
	v_rsq_f32_e32 v4, v4
	s_nop 0
	v_mul_f32_e32 v5, 0x45800000, v4
	v_cndmask_b32_e32 v22, v4, v5, vcc
	ds_read_b128 v[4:7], v24 offset:33280
	s_waitcnt lgkmcnt(0)
	v_pk_mul_f32 v[4:5], v[4:5], v[22:23] op_sel_hi:[1,0]
	v_pk_mul_f32 v[6:7], v[6:7], v[22:23] op_sel_hi:[1,0]
	s_waitcnt vmcnt(2)
	v_pk_mul_f32 v[4:5], v[36:37], v[4:5]
	v_pk_mul_f32 v[6:7], v[38:39], v[6:7]
	v_pk_mul_f32 v[36:37], v[2:3], v[22:23] op_sel_hi:[1,0]
	v_pk_mul_f32 v[38:39], v[0:1], v[22:23] op_sel_hi:[1,0]
	v_pk_mul_f32 v[34:35], v[34:35], v[36:37]
	v_pk_mul_f32 v[32:33], v[32:33], v[38:39]
	s_waitcnt vmcnt(0)
	v_pk_mul_f32 v[4:5], v[44:45], v[4:5]
	v_pk_mul_f32 v[6:7], v[46:47], v[6:7]
	v_cndmask_b32_e64 v37, v5, -v5, s[40:41]
	v_cndmask_b32_e64 v36, v4, -v4, s[40:41]
	v_cndmask_b32_e64 v5, v7, -v7, s[40:41]
	v_cndmask_b32_e64 v4, v6, -v6, s[40:41]
	v_pk_fma_f32 v[4:5], v[42:43], v[34:35], v[4:5]
	v_pk_fma_f32 v[6:7], v[40:41], v[32:33], v[36:37]

.LBB0_435:
	s_waitcnt lgkmcnt(0)
	v_pk_mul_f32 v[0:1], s[84:85], v[6:7]
	v_pk_mul_f32 v[2:3], s[84:85], v[4:5]
	v_cvt_pk_bf16_f32 v0, v0, v1
	v_cvt_pk_bf16_f32 v1, v2, v3
	v_ashrrev_i32_e32 v2, 31, v27
	v_mul_lo_u32 v4, s55, v27
	v_mul_lo_u32 v5, s54, v2
	v_mad_u64_u32 v[2:3], s[14:15], s54, v27, 0
	v_add3_u32 v3, v3, v5, v4
	v_lshl_add_u64 v[2:3], v[2:3], 1, v[20:21]
	global_store_dwordx2 v[2:3], v[0:1], off
	ds_read_b128 v[0:3], v25 offset:49920
	v_add_u32_e32 v26, 0xb0, v26
	s_cmp_lt_i32 s5, 2
	s_mov_b64 s[14:15], -1
	s_cbranch_scc1 .LBB0_439
	s_cmp_eq_u32 s5, 2
	v_add_u32_e32 v28, 0x300, v30
	v_and_b32_e32 v28, 0x3f0, v28
	v_cmp_gt_i32_e32 vcc, s33, v26
	global_load_dwordx4 v[32:35], v[18:19], off
	global_load_dwordx4 v[36:39], v[16:17], off
	v_cndmask_b32_e32 v27, v189, v190, vcc
	v_and_b32_e32 v27, v27, v26
	v_lshrrev_b32_e32 v27, 2, v27
	v_cndmask_b32_e64 v27, v28, v27, s[46:47]
	v_lshlrev_b32_e32 v168, 2, v27
	v_lshl_add_u64 v[40:41], v[12:13], 0, v[168:169]
	v_lshl_add_u64 v[44:45], v[14:15], 0, v[168:169]
	global_load_dwordx4 v[40:43], v[40:41], off
	global_load_dwordx4 v[44:47], v[44:45], off
	s_waitcnt lgkmcnt(0)
	v_mov_b32_e32 v5, v3
	v_mov_b32_e32 v4, v2
	v_mov_b32_e32 v7, v1
	v_mov_b32_e32 v6, v0
	s_cbranch_scc0 .LBB0_438
	v_pk_mul_f32 v[6:7], v[0:1], v[0:1]
	v_pk_mul_f32 v[4:5], v[2:3], v[2:3]
	v_add_f32_e32 v6, v6, v7
	v_add_f32_e32 v4, v4, v6
	v_and_b32_e32 v6, 64, v182
	v_add_f32_e32 v4, v5, v4
	v_xor_b32_e32 v5, 1, v182
	v_add_u32_e32 v6, 64, v6
	v_cmp_lt_i32_e32 vcc, v5, v6
	v_cndmask_b32_e32 v5, v182, v5, vcc
	v_lshlrev_b32_e32 v5, 2, v5
	ds_bpermute_b32 v5, v5, v4
	s_waitcnt lgkmcnt(0)
	v_add_f32_e32 v4, v4, v5
	v_xor_b32_e32 v5, 2, v182
	v_cmp_lt_i32_e32 vcc, v5, v6
	s_nop 1
	v_cndmask_b32_e32 v5, v182, v5, vcc
	v_lshlrev_b32_e32 v5, 2, v5
	ds_bpermute_b32 v5, v5, v4
	s_waitcnt lgkmcnt(0)
	v_add_f32_e32 v4, v4, v5
	v_xor_b32_e32 v5, 4, v182
	v_cmp_lt_i32_e32 vcc, v5, v6
	s_nop 1
	v_cndmask_b32_e32 v5, v182, v5, vcc
	v_lshlrev_b32_e32 v5, 2, v5
	ds_bpermute_b32 v5, v5, v4
	s_waitcnt lgkmcnt(0)
	v_add_f32_e32 v4, v4, v5
	v_xor_b32_e32 v5, 8, v182
	v_cmp_lt_i32_e32 vcc, v5, v6
	s_nop 1
	v_cndmask_b32_e32 v5, v182, v5, vcc
	v_lshlrev_b32_e32 v5, 2, v5
	ds_bpermute_b32 v5, v5, v4
	s_waitcnt lgkmcnt(0)
	v_add_f32_e32 v4, v4, v5
	v_fmamk_f32 v4, v4, 0x3c800000, v172
	v_cmp_gt_f32_e32 vcc, s4, v4
	v_mul_f32_e32 v5, 0x4b800000, v4
	s_nop 0
	v_cndmask_b32_e32 v4, v4, v5, vcc
	v_rsq_f32_e32 v4, v4
	s_nop 0
	v_mul_f32_e32 v5, 0x45800000, v4
	v_cndmask_b32_e32 v22, v4, v5, vcc
	ds_read_b128 v[4:7], v24 offset:49920
	s_waitcnt lgkmcnt(0)
	v_pk_mul_f32 v[4:5], v[4:5], v[22:23] op_sel_hi:[1,0]
	v_pk_mul_f32 v[6:7], v[6:7], v[22:23] op_sel_hi:[1,0]
	s_waitcnt vmcnt(2)
	v_pk_mul_f32 v[4:5], v[36:37], v[4:5]
	v_pk_mul_f32 v[6:7], v[38:39], v[6:7]
	v_pk_mul_f32 v[36:37], v[2:3], v[22:23] op_sel_hi:[1,0]
	v_pk_mul_f32 v[38:39], v[0:1], v[22:23] op_sel_hi:[1,0]
	v_pk_mul_f32 v[34:35], v[34:35], v[36:37]
	v_pk_mul_f32 v[32:33], v[32:33], v[38:39]
	s_waitcnt vmcnt(0)
	v_pk_mul_f32 v[4:5], v[44:45], v[4:5]
	v_pk_mul_f32 v[6:7], v[46:47], v[6:7]
	v_cndmask_b32_e64 v37, v5, -v5, s[40:41]
	v_cndmask_b32_e64 v36, v4, -v4, s[40:41]
	v_cndmask_b32_e64 v5, v7, -v7, s[40:41]
	v_cndmask_b32_e64 v4, v6, -v6, s[40:41]
	v_pk_fma_f32 v[4:5], v[42:43], v[34:35], v[4:5]
	v_pk_fma_f32 v[6:7], v[40:41], v[32:33], v[36:37]
